# placement check after the first barrier issues all 32 census loads together (one memory round trip instead of two)
# baseline (speedup 1.0000x reference)
.LBB0_115:
	v_cmp_eq_u32_e32 vcc, 0, v0
	s_and_saveexec_b64 s[2:3], vcc
	s_cbranch_execz .Llb_chk_done
	v_readlane_b32 s4, v254, 12
	v_readlane_b32 s5, v254, 13
	v_mov_b32_e32 v1, 0x2404
	s_nop 4
	global_load_dword v2, v1, s[4:5] sc1
	global_load_dword v3, v1, s[4:5] offset:256 sc1
	global_load_dword v4, v1, s[4:5] offset:512 sc1
	global_load_dword v5, v1, s[4:5] offset:768 sc1
	global_load_dword v6, v1, s[4:5] offset:1024 sc1
	global_load_dword v7, v1, s[4:5] offset:1280 sc1
	global_load_dword v8, v1, s[4:5] offset:1536 sc1
	global_load_dword v9, v1, s[4:5] offset:1792 sc1
	global_load_dword v10, v1, s[4:5] offset:2048 sc1
	global_load_dword v11, v1, s[4:5] offset:2304 sc1
	global_load_dword v12, v1, s[4:5] offset:2560 sc1
	global_load_dword v13, v1, s[4:5] offset:2816 sc1
	global_load_dword v14, v1, s[4:5] offset:3072 sc1
	global_load_dword v15, v1, s[4:5] offset:3328 sc1
	global_load_dword v16, v1, s[4:5] offset:3584 sc1
	global_load_dword v17, v1, s[4:5] offset:3840 sc1
	v_mov_b32_e32 v35, 0x400
	global_load_dword v36, v35, s[4:5] sc1
	global_load_dword v37, v35, s[4:5] offset:256 sc1
	global_load_dword v38, v35, s[4:5] offset:512 sc1
	global_load_dword v39, v35, s[4:5] offset:768 sc1
	global_load_dword v40, v35, s[4:5] offset:1024 sc1
	global_load_dword v41, v35, s[4:5] offset:1280 sc1
	global_load_dword v42, v35, s[4:5] offset:1536 sc1
	global_load_dword v43, v35, s[4:5] offset:1792 sc1
	global_load_dword v44, v35, s[4:5] offset:2048 sc1
	global_load_dword v45, v35, s[4:5] offset:2304 sc1
	global_load_dword v46, v35, s[4:5] offset:2560 sc1
	global_load_dword v47, v35, s[4:5] offset:2816 sc1
	global_load_dword v48, v35, s[4:5] offset:3072 sc1
	global_load_dword v49, v35, s[4:5] offset:3328 sc1
	global_load_dword v50, v35, s[4:5] offset:3584 sc1
	global_load_dword v51, v35, s[4:5] offset:3840 sc1
	s_waitcnt vmcnt(0)
	v_mov_b32_e32 v19, 0
	v_add_u32_e32 v18, -1, v2
	v_and_b32_e32 v18, v18, v2
	v_or_b32_e32 v19, v19, v18
	v_add_u32_e32 v18, -1, v3
	v_and_b32_e32 v18, v18, v3
	v_or_b32_e32 v19, v19, v18
	v_add_u32_e32 v18, -1, v4
	v_and_b32_e32 v18, v18, v4
	v_or_b32_e32 v19, v19, v18
	v_add_u32_e32 v18, -1, v5
	v_and_b32_e32 v18, v18, v5
	v_or_b32_e32 v19, v19, v18
	v_add_u32_e32 v18, -1, v6
	v_and_b32_e32 v18, v18, v6
	v_or_b32_e32 v19, v19, v18
	v_add_u32_e32 v18, -1, v7
	v_and_b32_e32 v18, v18, v7
	v_or_b32_e32 v19, v19, v18
	v_add_u32_e32 v18, -1, v8
	v_and_b32_e32 v18, v18, v8
	v_or_b32_e32 v19, v19, v18
	v_add_u32_e32 v18, -1, v9
	v_and_b32_e32 v18, v18, v9
	v_or_b32_e32 v19, v19, v18
	v_add_u32_e32 v18, -1, v10
	v_and_b32_e32 v18, v18, v10
	v_or_b32_e32 v19, v19, v18
	v_add_u32_e32 v18, -1, v11
	v_and_b32_e32 v18, v18, v11
	v_or_b32_e32 v19, v19, v18
	v_add_u32_e32 v18, -1, v12
	v_and_b32_e32 v18, v18, v12
	v_or_b32_e32 v19, v19, v18
	v_add_u32_e32 v18, -1, v13
	v_and_b32_e32 v18, v18, v13
	v_or_b32_e32 v19, v19, v18
	v_add_u32_e32 v18, -1, v14
	v_and_b32_e32 v18, v18, v14
	v_or_b32_e32 v19, v19, v18
	v_add_u32_e32 v18, -1, v15
	v_and_b32_e32 v18, v18, v15
	v_or_b32_e32 v19, v19, v18
	v_add_u32_e32 v18, -1, v16
	v_and_b32_e32 v18, v18, v16
	v_or_b32_e32 v19, v19, v18
	v_add_u32_e32 v18, -1, v17
	v_and_b32_e32 v18, v18, v17
	v_or_b32_e32 v19, v19, v18
	v_subrev_u32_e32 v18, 32, v36
	v_mul_lo_u32 v18, v18, v36
	v_or_b32_e32 v19, v19, v18
	v_subrev_u32_e32 v18, 32, v37
	v_mul_lo_u32 v18, v18, v37
	v_or_b32_e32 v19, v19, v18
	v_subrev_u32_e32 v18, 32, v38
	v_mul_lo_u32 v18, v18, v38
	v_or_b32_e32 v19, v19, v18
	v_subrev_u32_e32 v18, 32, v39
	v_mul_lo_u32 v18, v18, v39
	v_or_b32_e32 v19, v19, v18
	v_subrev_u32_e32 v18, 32, v40
	v_mul_lo_u32 v18, v18, v40
	v_or_b32_e32 v19, v19, v18
	v_subrev_u32_e32 v18, 32, v41
	v_mul_lo_u32 v18, v18, v41
	v_or_b32_e32 v19, v19, v18
	v_subrev_u32_e32 v18, 32, v42
	v_mul_lo_u32 v18, v18, v42
	v_or_b32_e32 v19, v19, v18
	v_subrev_u32_e32 v18, 32, v43
	v_mul_lo_u32 v18, v18, v43
	v_or_b32_e32 v19, v19, v18
	v_subrev_u32_e32 v18, 32, v44
	v_mul_lo_u32 v18, v18, v44
	v_or_b32_e32 v19, v19, v18
	v_subrev_u32_e32 v18, 32, v45
	v_mul_lo_u32 v18, v18, v45
	v_or_b32_e32 v19, v19, v18
	v_subrev_u32_e32 v18, 32, v46
	v_mul_lo_u32 v18, v18, v46
	v_or_b32_e32 v19, v19, v18
	v_subrev_u32_e32 v18, 32, v47
	v_mul_lo_u32 v18, v18, v47
	v_or_b32_e32 v19, v19, v18
	v_subrev_u32_e32 v18, 32, v48
	v_mul_lo_u32 v18, v18, v48
	v_or_b32_e32 v19, v19, v18
	v_subrev_u32_e32 v18, 32, v49
	v_mul_lo_u32 v18, v18, v49
	v_or_b32_e32 v19, v19, v18
	v_subrev_u32_e32 v18, 32, v50
	v_mul_lo_u32 v18, v18, v50
	v_or_b32_e32 v19, v19, v18
	v_subrev_u32_e32 v18, 32, v51
	v_mul_lo_u32 v18, v18, v51
	v_or_b32_e32 v19, v19, v18
	v_mov_b32_e32 v23, s25
	v_xor_b32_e32 v23, 0x100, v23
	v_or_b32_e32 v19, v19, v23
	v_mov_b32_e32 v20, s88
	v_cmp_eq_u32_e32 vcc, 0, v19
	s_nop 1
	v_cndmask_b32_e64 v19, 0, 1, vcc
	ds_write_b32 v20, v19 offset:8
	s_waitcnt lgkmcnt(0)
